# attention tile loop rewritten as a two-half ping-pong: MFMA slot (PV then S, all LDS reads riding in MFMA gaps) beside the partner wave's softmax slot, two-tile-deep K/V prefetch with two staging regi
# speedup vs baseline: 1.0837x; 1.0103x over previous
.LBB0_55:
	s_andn2_saveexec_b64 s[54:55], s[54:55]
	ds_write_b128 v197, v[80:83] offset:128
	s_or_b64 exec, exec, s[54:55]
	v_add_f32_e32 v1, v1, v126
	v_fmamk_f32 v1, v1, 0x3c2aaaab, v207
	v_rsq_f32_e32 v1, v1
	ds_write_b128 v198, v[2:5] offset:13312
	s_waitcnt lgkmcnt(0)
	s_barrier
	v_mul_f32_e32 v66, 0x3e16c740, v1
	s_waitcnt lgkmcnt(6)
	v_pk_mul_f32 v[38:39], v[66:67], v[38:39] op_sel_hi:[0,1]
	v_pk_mul_f32 v[38:39], v[38:39], v[110:111]
	v_pk_mul_f32 v[44:45], v[66:67], v[44:45] op_sel_hi:[0,1]
	v_pk_mul_f32 v[44:45], v[44:45], v[86:87]
	v_cvt_pk_bf16_f32 v86, v38, v39
	v_pk_mul_f32 v[38:39], v[66:67], v[106:107] op_sel_hi:[0,1]
	s_waitcnt lgkmcnt(5)
	v_pk_mul_f32 v[30:31], v[38:39], v[30:31]
	v_pk_mul_f32 v[38:39], v[66:67], v[108:109] op_sel_hi:[0,1]
	s_waitcnt lgkmcnt(3)
	v_pk_mul_f32 v[22:23], v[38:39], v[22:23]
	v_pk_mul_f32 v[46:47], v[66:67], v[46:47] op_sel_hi:[0,1]
	s_waitcnt vmcnt(0)
	v_pk_mul_f32 v[38:39], v[22:23], v[34:35]
	v_pk_mul_f32 v[42:43], v[66:67], v[42:43] op_sel_hi:[0,1]
	v_pk_fma_f32 v[38:39], v[30:31], v[26:27], v[38:39] neg_lo:[0,0,1] neg_hi:[0,0,1]
	v_pk_mul_f32 v[30:31], v[30:31], v[34:35]
	v_pk_mul_f32 v[40:41], v[66:67], v[40:41] op_sel_hi:[0,1]
	v_pk_fma_f32 v[22:23], v[22:23], v[26:27], v[30:31]
	v_pk_mul_f32 v[30:31], v[66:67], v[104:105] op_sel_hi:[0,1]
	v_pk_mul_f32 v[26:27], v[66:67], v[102:103] op_sel_hi:[0,1]
	v_pk_mul_f32 v[24:25], v[30:31], v[24:25]
	v_pk_mul_f32 v[26:27], v[26:27], v[32:33]
	v_pk_mul_f32 v[30:31], v[24:25], v[36:37]
	v_pk_mul_f32 v[68:69], v[66:67], v[70:71] op_sel_hi:[0,1]
	v_pk_fma_f32 v[30:31], v[26:27], v[28:29], v[30:31] neg_lo:[0,0,1] neg_hi:[0,0,1]
	v_pk_mul_f32 v[26:27], v[26:27], v[36:37]
	v_pk_mul_f32 v[62:63], v[66:67], v[62:63] op_sel_hi:[0,1]
	v_pk_fma_f32 v[24:25], v[24:25], v[28:29], v[26:27]
	v_pk_mul_f32 v[26:27], v[66:67], v[78:79] op_sel_hi:[0,1]
	v_pk_mul_f32 v[14:15], v[26:27], v[14:15]
	v_pk_mul_f32 v[26:27], v[66:67], v[100:101] op_sel_hi:[0,1]
	s_waitcnt lgkmcnt(2)
	v_pk_mul_f32 v[10:11], v[26:27], v[10:11]
	v_pk_mul_f32 v[70:71], v[66:67], v[72:73] op_sel_hi:[0,1]
	v_pk_mul_f32 v[26:27], v[10:11], v[18:19]
	v_pk_mul_f32 v[64:65], v[66:67], v[64:65] op_sel_hi:[0,1]
	v_pk_fma_f32 v[26:27], v[14:15], v[6:7], v[26:27] neg_lo:[0,0,1] neg_hi:[0,0,1]
	v_pk_mul_f32 v[14:15], v[14:15], v[18:19]
	v_pk_mul_f32 v[58:59], v[66:67], v[58:59] op_sel_hi:[0,1]
	v_pk_fma_f32 v[6:7], v[10:11], v[6:7], v[14:15]
	v_pk_mul_f32 v[14:15], v[66:67], v[76:77] op_sel_hi:[0,1]
	v_pk_mul_f32 v[10:11], v[66:67], v[74:75] op_sel_hi:[0,1]
	v_pk_mul_f32 v[12:13], v[14:15], v[12:13]
	v_pk_mul_f32 v[10:11], v[10:11], v[16:17]
	v_pk_mul_f32 v[14:15], v[12:13], v[20:21]
	v_pk_mul_f32 v[54:55], v[66:67], v[54:55] op_sel_hi:[0,1]
	v_pk_fma_f32 v[14:15], v[10:11], v[8:9], v[14:15] neg_lo:[0,0,1] neg_hi:[0,0,1]
	v_pk_mul_f32 v[10:11], v[10:11], v[20:21]
	v_pk_mul_f32 v[60:61], v[66:67], v[60:61] op_sel_hi:[0,1]
	v_pk_mul_f32 v[56:57], v[66:67], v[56:57] op_sel_hi:[0,1]
	v_pk_mul_f32 v[50:51], v[66:67], v[50:51] op_sel_hi:[0,1]
	v_pk_mul_f32 v[46:47], v[46:47], v[114:115]
	v_pk_mul_f32 v[52:53], v[66:67], v[52:53] op_sel_hi:[0,1]
	v_pk_mul_f32 v[48:49], v[66:67], v[48:49] op_sel_hi:[0,1]
	v_pk_mul_f32 v[42:43], v[42:43], v[112:113]
	v_pk_mul_f32 v[40:41], v[40:41], v[84:85]
	v_pk_fma_f32 v[8:9], v[12:13], v[8:9], v[10:11]
	v_cvt_pk_bf16_f32 v103, v14, v15
	v_mov_b32_e32 v14, v0
	v_mov_b32_e32 v15, v0
	v_pk_mul_f32 v[68:69], v[68:69], v[124:125]
	v_pk_mul_f32 v[62:63], v[62:63], v[122:123]
	v_pk_mul_f32 v[70:71], v[70:71], v[90:91]
	v_pk_mul_f32 v[64:65], v[64:65], v[88:89]
	v_pk_mul_f32 v[58:59], v[58:59], v[120:121]
	v_pk_mul_f32 v[54:55], v[54:55], v[118:119]
	v_pk_mul_f32 v[60:61], v[60:61], v[94:95]
	v_pk_mul_f32 v[56:57], v[56:57], v[92:93]
	v_pk_mul_f32 v[50:51], v[50:51], v[116:117]
	v_pk_mul_f32 v[52:53], v[52:53], v[98:99]
	v_pk_mul_f32 v[48:49], v[48:49], v[96:97]
	v_cvt_pk_bf16_f32 v98, v46, v47
	v_cvt_pk_bf16_f32 v84, v42, v43
	v_cvt_pk_bf16_f32 v85, v44, v45
	v_cvt_pk_bf16_f32 v87, v40, v41
	v_cvt_pk_bf16_f32 v100, v38, v39
	v_cvt_pk_bf16_f32 v101, v30, v31
	v_cvt_pk_bf16_f32 v102, v26, v27
	v_cvt_pk_bf16_f32 v104, v22, v23
	v_cvt_pk_bf16_f32 v105, v24, v25
	v_cvt_pk_bf16_f32 v106, v6, v7
	v_cvt_pk_bf16_f32 v107, v8, v9
	s_lshl_b32 s48, s38, 2
	v_mov_b32_e32 v1, v0
	v_mov_b32_e32 v2, v0
	v_mov_b32_e32 v3, v0
	v_mov_b32_e32 v4, v0
	v_mov_b32_e32 v5, v0
	v_mov_b32_e32 v6, v0
	v_mov_b32_e32 v7, v0
	v_mov_b32_e32 v8, v0
	v_mov_b32_e32 v9, v0
	v_mov_b32_e32 v10, v0
	v_mov_b32_e32 v11, v0
	v_mov_b32_e32 v12, v0
	v_mov_b32_e32 v13, v0
	v_mov_b64_e32 v[30:31], v[14:15]
	v_mov_b64_e32 v[46:47], v[14:15]
	v_cvt_pk_bf16_f32 v88, v68, v69
	v_cvt_pk_bf16_f32 v89, v70, v71
	v_cvt_pk_bf16_f32 v90, v62, v63
	v_cvt_pk_bf16_f32 v91, v64, v65
	v_cvt_pk_bf16_f32 v92, v58, v59
	v_cvt_pk_bf16_f32 v93, v60, v61
	v_cvt_pk_bf16_f32 v94, v54, v55
	v_cvt_pk_bf16_f32 v95, v56, v57
	v_cvt_pk_bf16_f32 v96, v50, v51
	v_cvt_pk_bf16_f32 v97, v52, v53
	v_cvt_pk_bf16_f32 v99, v48, v49
	s_add_i32 s48, s48, s26
	s_mov_b32 s49, 0
	v_mov_b32_e32 v151, 0
	v_mov_b64_e32 v[174:175], v[172:173]
	v_mov_b32_e32 v176, v228
	v_mov_b32_e32 v178, v205
	v_mov_b32_e32 v180, v204
	v_mov_b64_e32 v[182:183], v[146:147]
	v_mov_b64_e32 v[28:29], v[12:13]
	v_mov_b64_e32 v[26:27], v[10:11]
	v_mov_b64_e32 v[24:25], v[8:9]
	v_mov_b64_e32 v[22:23], v[6:7]
	v_mov_b64_e32 v[20:21], v[4:5]
	v_mov_b64_e32 v[18:19], v[2:3]
	v_mov_b64_e32 v[16:17], v[0:1]
	v_mov_b64_e32 v[44:45], v[12:13]
	v_mov_b64_e32 v[42:43], v[10:11]
	v_mov_b64_e32 v[40:41], v[8:9]
	v_mov_b64_e32 v[38:39], v[6:7]
	v_mov_b64_e32 v[36:37], v[4:5]
	v_mov_b64_e32 v[34:35], v[2:3]
	v_mov_b64_e32 v[32:33], v[0:1]
	v_lshlrev_b32_e32 v1, 4, v164
	v_add_u32_e32 v1, 0x14000, v1
	ds_write_b128 v1, v[194:197]
	ds_write_b128 v1, v[198:201] offset:8192
	ds_write_b128 v1, v[202:205] offset:16384
	s_waitcnt lgkmcnt(0)
	s_cmp_lg_u64 s[42:43], 0
	s_cbranch_scc1 .Latt2_h1
	global_load_dwordx4 v[194:197], v[182:183], off
	v_ashrrev_i32_e32 v177, 31, v176
	v_lshlrev_b64 v[202:203], 6, v[176:177]
	v_lshl_add_u64 v[202:203], v[144:145], 0, v[202:203]
	global_load_dwordx4 v[198:201], v[202:203], off
	global_load_dwordx4 v[202:205], v[174:175], off
	v_lshl_add_u64 v[182:183], v[182:183], 0, s[10:11]
	v_add_u32_e32 v180, 0x400, v180
	v_add_u32_e32 v178, 64, v178
	v_add_u32_e32 v176, 64, v176
	v_lshl_add_u64 v[174:175], v[174:175], 0, s[12:13]
	global_load_dwordx4 v[2:5], v[182:183], off
	v_ashrrev_i32_e32 v177, 31, v176
	v_lshlrev_b64 v[6:7], 6, v[176:177]
	v_lshl_add_u64 v[6:7], v[144:145], 0, v[6:7]
	global_load_dwordx4 v[80:83], v[6:7], off
	global_load_dwordx4 v[6:9], v[174:175], off
	v_lshl_add_u64 v[182:183], v[182:183], 0, s[10:11]
	v_add_u32_e32 v180, 0x400, v180
	v_add_u32_e32 v178, 64, v178
	v_add_u32_e32 v176, 64, v176
	v_lshl_add_u64 v[174:175], v[174:175], 0, s[12:13]
.Latt2_h0_loop:
	s_cmp_gt_i32 s49, s48
	s_cbranch_scc1 .Latt2_h0p0_xin
	s_bitcmp1_b32 s49, 0
	s_cselect_b32 s53, 0x5900, 0
	v_add3_u32 v157, s53, v190, v191
	v_add_u32_e32 v1, s53, v193
	v_add3_u32 v229, s53, v192, v191
	s_cmp_eq_u32 s49, 0
	s_cbranch_scc1 .Latt2_h0p0_xt0
	ds_read_b128 v[72:75], v157
	ds_read_b128 v[56:59], v157 offset:6656
	v_mfma_f32_32x32x16_bf16 v[32:47], v[128:131], v[64:67], v[32:47]
	ds_read_b128 v[230:233], v157 offset:32
	ds_read_b128 v[234:237], v157 offset:6688
	v_mfma_f32_32x32x16_bf16 v[16:31], v[210:213], v[64:67], v[16:31]
	ds_read_b128 v[238:241], v157 offset:64
	ds_read_b128 v[242:245], v157 offset:6720
	v_mfma_f32_32x32x16_bf16 v[32:47], v[124:127], v[68:71], v[32:47]
	ds_read_b128 v[246:249], v157 offset:96
	ds_read_b128 v[250:253], v157 offset:6752
	v_mfma_f32_32x32x16_bf16 v[16:31], v[120:123], v[68:71], v[16:31]
	ds_read_b128 v[214:217], v157 offset:128
	ds_read_b128 v[128:131], v157 offset:6784
	v_mfma_f32_32x32x16_bf16 v[32:47], v[116:119], v[48:51], v[32:47]
	ds_read_b128 v[210:213], v157 offset:160
	v_mfma_f32_32x32x16_bf16 v[16:31], v[112:115], v[48:51], v[16:31]
	ds_read_b128 v[124:127], v157 offset:6816
	v_mfma_f32_32x32x16_bf16 v[32:47], v[108:111], v[52:55], v[32:47]
	v_mfma_f32_32x32x16_bf16 v[16:31], v[10:13], v[52:55], v[16:31]
	s_branch .Latt2_h0p0_xs
.Latt2_h0p0_xt0:
	ds_read_b128 v[72:75], v157
	ds_read_b128 v[56:59], v157 offset:6656
	ds_read_b128 v[230:233], v157 offset:32
	ds_read_b128 v[234:237], v157 offset:6688
	ds_read_b128 v[238:241], v157 offset:64
	ds_read_b128 v[242:245], v157 offset:6720
	ds_read_b128 v[246:249], v157 offset:96
	ds_read_b128 v[250:253], v157 offset:6752
	ds_read_b128 v[214:217], v157 offset:128
	ds_read_b128 v[128:131], v157 offset:6784
	ds_read_b128 v[210:213], v157 offset:160
	ds_read_b128 v[124:127], v157 offset:6816
.Latt2_h0p0_xs:
	s_waitcnt lgkmcnt(11)
	v_mfma_f32_32x32x16_bf16 v[64:79], v[72:75], v[88:91], 0
	ds_read_b128 v[10:13], v229 offset:18016
	ds_read_b128 v[108:111], v229 offset:13408
	s_waitcnt lgkmcnt(12)
	v_mfma_f32_32x32x16_bf16 v[48:63], v[56:59], v[88:91], 0
	ds_read_b128 v[112:115], v229 offset:17984
	ds_read_b128 v[116:119], v229 offset:13376
	s_waitcnt lgkmcnt(13)
	v_mfma_f32_32x32x16_bf16 v[64:79], v[230:233], v[92:95], v[64:79]
	ds_read_b128 v[120:123], v229 offset:17952
	ds_read_b128 v[230:233], v1 offset:22528
	s_waitcnt lgkmcnt(14)
	v_mfma_f32_32x32x16_bf16 v[48:63], v[234:237], v[92:95], v[48:63]
	ds_read_b128 v[234:237], v1 offset:22544
	s_waitcnt lgkmcnt(14)
	v_mfma_f32_32x32x16_bf16 v[64:79], v[238:241], v[96:99], v[64:79]
	ds_read_b128 v[238:241], v1 offset:22592
	s_waitcnt lgkmcnt(14)
	v_mfma_f32_32x32x16_bf16 v[48:63], v[242:245], v[96:99], v[48:63]
	ds_read_b128 v[242:245], v1 offset:22608
	s_waitcnt lgkmcnt(14)
	v_mfma_f32_32x32x16_bf16 v[64:79], v[246:249], v[84:87], v[64:79]
	ds_read_b128 v[246:249], v1 offset:22656
	s_waitcnt lgkmcnt(14)
	v_mfma_f32_32x32x16_bf16 v[48:63], v[250:253], v[84:87], v[48:63]
	ds_read_b128 v[250:253], v1 offset:22672
	s_waitcnt lgkmcnt(14)
	v_mfma_f32_32x32x16_bf16 v[64:79], v[214:217], v[100:103], v[64:79]
	ds_read_b128 v[214:217], v1 offset:22720
	s_waitcnt lgkmcnt(14)
	v_mfma_f32_32x32x16_bf16 v[48:63], v[128:131], v[100:103], v[48:63]
	ds_read_b128 v[128:131], v229 offset:13312
	s_waitcnt lgkmcnt(14)
	v_mfma_f32_32x32x16_bf16 v[64:79], v[210:213], v[104:107], v[64:79]
	ds_read_b128 v[210:213], v229 offset:17920
	s_waitcnt lgkmcnt(14)
	v_mfma_f32_32x32x16_bf16 v[48:63], v[124:127], v[104:107], v[48:63]
	ds_read_b128 v[124:127], v229 offset:13344
	s_branch .Latt2_h0p0_xend
.Latt2_h0p0_xin:
	s_add_i32 s53, s48, 1
	s_cmp_lg_u32 s49, s53
	s_cbranch_scc1 .Latt2_h0p0_xend
	s_waitcnt lgkmcnt(0)
	v_mfma_f32_32x32x16_bf16 v[32:47], v[128:131], v[64:67], v[32:47]
	v_mfma_f32_32x32x16_bf16 v[16:31], v[210:213], v[64:67], v[16:31]
	v_mfma_f32_32x32x16_bf16 v[32:47], v[124:127], v[68:71], v[32:47]
	v_mfma_f32_32x32x16_bf16 v[16:31], v[120:123], v[68:71], v[16:31]
	v_mfma_f32_32x32x16_bf16 v[32:47], v[116:119], v[48:51], v[32:47]
	v_mfma_f32_32x32x16_bf16 v[16:31], v[112:115], v[48:51], v[16:31]
	v_mfma_f32_32x32x16_bf16 v[32:47], v[108:111], v[52:55], v[32:47]
	v_mfma_f32_32x32x16_bf16 v[16:31], v[10:13], v[52:55], v[16:31]
.Latt2_h0p0_xend:
	s_barrier
	s_cmp_gt_i32 s49, s48
	s_cbranch_scc1 .Latt2_yskip_h0p0
	s_bitcmp1_b32 s49, 0
	s_cselect_b32 s53, 0x5900, 0
	v_add_u32_e32 v1, s53, v193
	s_waitcnt lgkmcnt(0)
	s_nop 3
	v_fma_f32 v64, v64, v230, -v165
	v_fma_f32 v65, v65, v231, -v165
	v_fma_f32 v66, v66, v232, -v165
	v_fma_f32 v67, v67, v233, -v165
	ds_read_b128 v[230:233], v1 offset:22736
	v_fma_f32 v68, v68, v234, -v165
	v_fma_f32 v69, v69, v235, -v165
	v_fma_f32 v70, v70, v236, -v165
	v_fma_f32 v71, v71, v237, -v165
	v_fma_f32 v72, v72, v238, -v165
	v_fma_f32 v73, v73, v239, -v165
	v_fma_f32 v74, v74, v240, -v165
	v_fma_f32 v75, v75, v241, -v165
	v_fma_f32 v76, v76, v242, -v165
	v_fma_f32 v77, v77, v243, -v165
	v_fma_f32 v78, v78, v244, -v165
	v_fma_f32 v79, v79, v245, -v165
	v_fma_f32 v48, v48, v246, -v165
	v_fma_f32 v49, v49, v247, -v165
	v_fma_f32 v50, v50, v248, -v165
	v_fma_f32 v51, v51, v249, -v165
	v_fma_f32 v52, v52, v250, -v165
	v_fma_f32 v53, v53, v251, -v165
	v_fma_f32 v54, v54, v252, -v165
	v_fma_f32 v55, v55, v253, -v165
	v_fma_f32 v56, v56, v214, -v165
	v_fma_f32 v57, v57, v215, -v165
	v_fma_f32 v58, v58, v216, -v165
	v_fma_f32 v59, v59, v217, -v165
	v_exp_f32_e32 v64, v64
	v_exp_f32_e32 v65, v65
	v_exp_f32_e32 v66, v66
	v_exp_f32_e32 v67, v67
	v_exp_f32_e32 v68, v68
	v_exp_f32_e32 v69, v69
	v_exp_f32_e32 v70, v70
	v_exp_f32_e32 v71, v71
	v_exp_f32_e32 v72, v72
	v_exp_f32_e32 v73, v73
	v_exp_f32_e32 v74, v74
	v_exp_f32_e32 v75, v75
	v_exp_f32_e32 v76, v76
	v_exp_f32_e32 v77, v77
	v_exp_f32_e32 v78, v78
	v_exp_f32_e32 v79, v79
	s_waitcnt lgkmcnt(0)
	v_fma_f32 v60, v60, v230, -v165
	v_fma_f32 v61, v61, v231, -v165
	v_fma_f32 v62, v62, v232, -v165
	v_fma_f32 v63, v63, v233, -v165
	v_exp_f32_e32 v48, v48
	v_exp_f32_e32 v49, v49
	v_exp_f32_e32 v50, v50
	v_exp_f32_e32 v51, v51
	v_exp_f32_e32 v52, v52
	v_exp_f32_e32 v53, v53
	v_exp_f32_e32 v54, v54
	v_exp_f32_e32 v55, v55
	v_exp_f32_e32 v56, v56
	v_exp_f32_e32 v57, v57
	v_exp_f32_e32 v58, v58
	v_exp_f32_e32 v59, v59
	v_exp_f32_e32 v60, v60
	v_exp_f32_e32 v61, v61
	v_exp_f32_e32 v62, v62
	v_exp_f32_e32 v63, v63
	v_add_f32_e32 v234, v64, v48
	v_add_f32_e32 v235, v65, v49
	v_add_f32_e32 v236, v66, v50
	v_add_f32_e32 v237, v67, v51
	v_add_f32_e32 v238, v68, v52
	v_add_f32_e32 v239, v69, v53
	v_add_f32_e32 v240, v70, v54
	v_add_f32_e32 v241, v71, v55
	v_add_f32_e32 v242, v72, v56
	v_add_f32_e32 v243, v73, v57
	v_add_f32_e32 v244, v74, v58
	v_add_f32_e32 v245, v75, v59
	v_add_f32_e32 v246, v76, v60
	v_add_f32_e32 v247, v77, v61
	v_add_f32_e32 v248, v78, v62
	v_add_f32_e32 v249, v79, v63
	v_add_f32_e32 v234, v234, v235
	v_add_f32_e32 v236, v236, v237
	v_add_f32_e32 v238, v238, v239
	v_add_f32_e32 v240, v240, v241
	v_add_f32_e32 v242, v242, v243
	v_add_f32_e32 v244, v244, v245
	v_add_f32_e32 v246, v246, v247
	v_add_f32_e32 v248, v248, v249
	v_add_f32_e32 v234, v234, v236
	v_add_f32_e32 v238, v238, v240
	v_add_f32_e32 v242, v242, v244
	v_add_f32_e32 v246, v246, v248
	v_add_f32_e32 v234, v234, v238
	v_add_f32_e32 v242, v242, v246
	v_add_f32_e32 v234, v234, v242
	v_cvt_pk_bf16_f32 v64, v64, v65
	v_cvt_pk_bf16_f32 v65, v66, v67
	v_cvt_pk_bf16_f32 v66, v68, v69
	v_cvt_pk_bf16_f32 v67, v70, v71
	v_cvt_pk_bf16_f32 v68, v72, v73
	v_cvt_pk_bf16_f32 v69, v74, v75
	v_cvt_pk_bf16_f32 v70, v76, v77
	v_cvt_pk_bf16_f32 v71, v78, v79
	v_cvt_pk_bf16_f32 v48, v48, v49
	v_cvt_pk_bf16_f32 v49, v50, v51
	v_cvt_pk_bf16_f32 v50, v52, v53
	v_cvt_pk_bf16_f32 v51, v54, v55
	v_cvt_pk_bf16_f32 v52, v56, v57
	v_cvt_pk_bf16_f32 v53, v58, v59
	v_cvt_pk_bf16_f32 v54, v60, v61
	v_cvt_pk_bf16_f32 v55, v62, v63
	v_add_f32_e32 v151, v151, v234
.Latt2_yskip_h0p0:
	s_cmp_ge_u32 s49, s47
	s_cbranch_scc1 .Latt2_h0p0_yend
	s_add_i32 s53, s49, 1
	s_cmp_lt_u32 s53, s47
	s_cbranch_scc1 .Latt2_P_3
	s_waitcnt vmcnt(0)
.Latt2_P_3:
	s_bitcmp0_b32 s49, 0
	s_cselect_b32 s53, 0x5900, 0
	v_add3_u32 v1, s53, v143, v134
	s_waitcnt vmcnt(4)
	ds_write_b128 v1, v[194:197]
	v_add3_u32 v1, s53, v188, v142
	ds_write_b128 v1, v[198:201] offset:128
	v_add3_u32 v1, s53, v189, v134
	s_waitcnt vmcnt(3)
	ds_write_b128 v1, v[202:205] offset:13312
	s_add_i32 s53, s49, 3
	s_cmp_gt_u32 s53, s47
	s_cbranch_scc1 .Latt2_h0p0_yend
	global_load_dwordx4 v[194:197], v[182:183], off
	v_ashrrev_i32_e32 v177, 31, v176
	v_lshlrev_b64 v[202:203], 6, v[176:177]
	v_lshl_add_u64 v[202:203], v[144:145], 0, v[202:203]
	global_load_dwordx4 v[198:201], v[202:203], off
	global_load_dwordx4 v[202:205], v[174:175], off
	v_lshl_add_u64 v[182:183], v[182:183], 0, s[10:11]
	v_add_u32_e32 v180, 0x400, v180
	v_add_u32_e32 v178, 64, v178
	v_add_u32_e32 v176, 64, v176
	v_lshl_add_u64 v[174:175], v[174:175], 0, s[12:13]
.Latt2_h0p0_yend:
	s_waitcnt lgkmcnt(0)
	s_barrier
	s_add_i32 s49, s49, 1
	s_cmp_gt_i32 s49, s48
	s_cbranch_scc1 .Latt2_h0p1_xin
	s_bitcmp1_b32 s49, 0
	s_cselect_b32 s53, 0x5900, 0
	v_add3_u32 v157, s53, v190, v191
	v_add_u32_e32 v1, s53, v193
	v_add3_u32 v229, s53, v192, v191
	ds_read_b128 v[72:75], v157
	ds_read_b128 v[56:59], v157 offset:6656
	v_mfma_f32_32x32x16_bf16 v[32:47], v[128:131], v[64:67], v[32:47]
	ds_read_b128 v[230:233], v157 offset:32
	ds_read_b128 v[234:237], v157 offset:6688
	v_mfma_f32_32x32x16_bf16 v[16:31], v[210:213], v[64:67], v[16:31]
	ds_read_b128 v[238:241], v157 offset:64
	ds_read_b128 v[242:245], v157 offset:6720
	v_mfma_f32_32x32x16_bf16 v[32:47], v[124:127], v[68:71], v[32:47]
	ds_read_b128 v[246:249], v157 offset:96
	ds_read_b128 v[250:253], v157 offset:6752
	v_mfma_f32_32x32x16_bf16 v[16:31], v[120:123], v[68:71], v[16:31]
	ds_read_b128 v[214:217], v157 offset:128
	ds_read_b128 v[128:131], v157 offset:6784
	v_mfma_f32_32x32x16_bf16 v[32:47], v[116:119], v[48:51], v[32:47]
	ds_read_b128 v[210:213], v157 offset:160
	v_mfma_f32_32x32x16_bf16 v[16:31], v[112:115], v[48:51], v[16:31]
	ds_read_b128 v[124:127], v157 offset:6816
	v_mfma_f32_32x32x16_bf16 v[32:47], v[108:111], v[52:55], v[32:47]
	v_mfma_f32_32x32x16_bf16 v[16:31], v[10:13], v[52:55], v[16:31]

.Latt2_P_5:
	s_bitcmp0_b32 s49, 0
	s_cselect_b32 s53, 0x5900, 0
	v_add3_u32 v1, s53, v143, v134
	s_waitcnt vmcnt(4)
	ds_write_b128 v1, v[2:5]
	v_add3_u32 v1, s53, v188, v142
	ds_write_b128 v1, v[80:83] offset:128
	v_add3_u32 v1, s53, v189, v134
	s_waitcnt vmcnt(3)
	ds_write_b128 v1, v[6:9] offset:13312
	s_add_i32 s53, s49, 3
	s_cmp_gt_u32 s53, s47
	s_cbranch_scc1 .Latt2_h0p1_yend
	global_load_dwordx4 v[2:5], v[182:183], off
	v_ashrrev_i32_e32 v177, 31, v176
	v_lshlrev_b64 v[6:7], 6, v[176:177]
	v_lshl_add_u64 v[6:7], v[144:145], 0, v[6:7]
	global_load_dwordx4 v[80:83], v[6:7], off
	global_load_dwordx4 v[6:9], v[174:175], off
	v_lshl_add_u64 v[182:183], v[182:183], 0, s[10:11]
	v_add_u32_e32 v180, 0x400, v180
	v_add_u32_e32 v178, 64, v178
	v_add_u32_e32 v176, 64, v176
	v_lshl_add_u64 v[174:175], v[174:175], 0, s[12:13]
.Latt2_h0p1_yend:
	s_waitcnt lgkmcnt(0)
	s_barrier
	s_add_i32 s49, s49, 1
	s_cmp_le_u32 s49, s47
	s_cbranch_scc1 .Latt2_h0_loop
	s_cmp_lg_u32 s48, s47
	s_cbranch_scc1 .Latt2_exit
	v_mfma_f32_32x32x16_bf16 v[32:47], v[128:131], v[64:67], v[32:47]
	v_mfma_f32_32x32x16_bf16 v[16:31], v[210:213], v[64:67], v[16:31]
	v_mfma_f32_32x32x16_bf16 v[32:47], v[124:127], v[68:71], v[32:47]
	v_mfma_f32_32x32x16_bf16 v[16:31], v[120:123], v[68:71], v[16:31]
	v_mfma_f32_32x32x16_bf16 v[32:47], v[116:119], v[48:51], v[32:47]
	v_mfma_f32_32x32x16_bf16 v[16:31], v[112:115], v[48:51], v[16:31]
	v_mfma_f32_32x32x16_bf16 v[32:47], v[108:111], v[52:55], v[32:47]
	v_mfma_f32_32x32x16_bf16 v[16:31], v[10:13], v[52:55], v[16:31]
	s_branch .Latt2_exit
.Latt2_h1:
	global_load_dwordx4 v[194:197], v[182:183], off
	s_cmp_lg_u64 s[44:45], 0
	s_cbranch_scc0 .Latt2_L_v_7
	v_ashrrev_i32_e32 v181, 31, v180
	v_lshl_add_u64 v[202:203], v[180:181], 2, s[8:9]
	v_ashrrev_i32_e32 v179, 31, v178
	global_load_dword v198, v[202:203], off
	v_lshl_add_u64 v[202:203], v[178:179], 2, s[22:23]
	global_load_dword v199, v[202:203], off
.Latt2_L_v_7:
	global_load_dwordx4 v[202:205], v[174:175], off
	v_lshl_add_u64 v[182:183], v[182:183], 0, s[10:11]
	v_add_u32_e32 v180, 0x400, v180
	v_add_u32_e32 v178, 64, v178
	v_add_u32_e32 v176, 64, v176
	v_lshl_add_u64 v[174:175], v[174:175], 0, s[12:13]
	global_load_dwordx4 v[2:5], v[182:183], off
	s_cmp_lg_u64 s[44:45], 0
	s_cbranch_scc0 .Latt2_L_v_8
	v_ashrrev_i32_e32 v181, 31, v180
	v_lshl_add_u64 v[6:7], v[180:181], 2, s[8:9]
	v_ashrrev_i32_e32 v179, 31, v178
	global_load_dword v153, v[6:7], off
	v_lshl_add_u64 v[6:7], v[178:179], 2, s[22:23]
	global_load_dword v155, v[6:7], off
.Latt2_L_v_8:
	global_load_dwordx4 v[6:9], v[174:175], off
	v_lshl_add_u64 v[182:183], v[182:183], 0, s[10:11]
	v_add_u32_e32 v180, 0x400, v180
	v_add_u32_e32 v178, 64, v178
	v_add_u32_e32 v176, 64, v176
	v_lshl_add_u64 v[174:175], v[174:175], 0, s[12:13]
	s_barrier

.Latt2_P_9:
	s_bitcmp0_b32 s49, 0
	s_cselect_b32 s53, 0x5900, 0
	v_add3_u32 v1, s53, v143, v134
	s_cmp_lg_u64 s[44:45], 0
	s_cbranch_scc0 .Latt2_S_o_9
	s_waitcnt vmcnt(5)
	ds_write_b128 v1, v[194:197]
	v_add_f32_e32 v1, v198, v199
	v_fmamk_f32 v1, v1, 0x3c2aaaab, v207
	v_rsq_f32_e32 v1, v1
	v_add_u32_e32 v157, s53, v187
	s_nop 0
	ds_write_b32 v157, v1 offset:21504
	s_waitcnt vmcnt(4)
	s_branch .Latt2_S_j_9
.Latt2_S_o_9:
	s_waitcnt vmcnt(3)
	ds_write_b128 v1, v[194:197]
	s_waitcnt vmcnt(2)
.Latt2_S_j_9:
	v_add3_u32 v1, s53, v189, v134
	ds_write_b128 v1, v[202:205] offset:13312
	s_add_i32 s53, s49, 3
	s_cmp_gt_u32 s53, s47
	s_cbranch_scc1 .Latt2_h1p0_xend
	global_load_dwordx4 v[194:197], v[182:183], off
	s_cmp_lg_u64 s[44:45], 0
	s_cbranch_scc0 .Latt2_L_v_10
	v_ashrrev_i32_e32 v181, 31, v180
	v_lshl_add_u64 v[202:203], v[180:181], 2, s[8:9]
	v_ashrrev_i32_e32 v179, 31, v178
	global_load_dword v198, v[202:203], off
	v_lshl_add_u64 v[202:203], v[178:179], 2, s[22:23]
	global_load_dword v199, v[202:203], off
.Latt2_L_v_10:
	global_load_dwordx4 v[202:205], v[174:175], off
	v_lshl_add_u64 v[182:183], v[182:183], 0, s[10:11]
	v_add_u32_e32 v180, 0x400, v180
	v_add_u32_e32 v178, 64, v178
	v_add_u32_e32 v176, 64, v176
	v_lshl_add_u64 v[174:175], v[174:175], 0, s[12:13]
.Latt2_h1p0_xend:
	s_waitcnt lgkmcnt(0)
	s_barrier
	s_cmp_gt_i32 s49, s48
	s_cbranch_scc1 .Latt2_yskip_h1p0
	s_bitcmp1_b32 s49, 0
	s_cselect_b32 s53, 0x5900, 0
	v_add_u32_e32 v1, s53, v193
	s_waitcnt lgkmcnt(0)
	s_nop 3
	v_fma_f32 v64, v64, v230, -v165
	v_fma_f32 v65, v65, v231, -v165
	v_fma_f32 v66, v66, v232, -v165
	v_fma_f32 v67, v67, v233, -v165
	ds_read_b128 v[230:233], v1 offset:22736
	v_fma_f32 v68, v68, v234, -v165
	v_fma_f32 v69, v69, v235, -v165
	v_fma_f32 v70, v70, v236, -v165
	v_fma_f32 v71, v71, v237, -v165
	v_fma_f32 v72, v72, v238, -v165
	v_fma_f32 v73, v73, v239, -v165
	v_fma_f32 v74, v74, v240, -v165
	v_fma_f32 v75, v75, v241, -v165
	v_fma_f32 v76, v76, v242, -v165
	v_fma_f32 v77, v77, v243, -v165
	v_fma_f32 v78, v78, v244, -v165
	v_fma_f32 v79, v79, v245, -v165
	v_fma_f32 v48, v48, v246, -v165
	v_fma_f32 v49, v49, v247, -v165
	v_fma_f32 v50, v50, v248, -v165
	v_fma_f32 v51, v51, v249, -v165
	v_fma_f32 v52, v52, v250, -v165
	v_fma_f32 v53, v53, v251, -v165
	v_fma_f32 v54, v54, v252, -v165
	v_fma_f32 v55, v55, v253, -v165
	v_fma_f32 v56, v56, v214, -v165
	v_fma_f32 v57, v57, v215, -v165
	v_fma_f32 v58, v58, v216, -v165
	v_fma_f32 v59, v59, v217, -v165
	v_exp_f32_e32 v64, v64
	v_exp_f32_e32 v65, v65
	v_exp_f32_e32 v66, v66
	v_exp_f32_e32 v67, v67
	v_exp_f32_e32 v68, v68
	v_exp_f32_e32 v69, v69
	v_exp_f32_e32 v70, v70
	v_exp_f32_e32 v71, v71
	v_exp_f32_e32 v72, v72
	v_exp_f32_e32 v73, v73
	v_exp_f32_e32 v74, v74
	v_exp_f32_e32 v75, v75
	v_exp_f32_e32 v76, v76
	v_exp_f32_e32 v77, v77
	v_exp_f32_e32 v78, v78
	v_exp_f32_e32 v79, v79
	s_waitcnt lgkmcnt(0)
	v_fma_f32 v60, v60, v230, -v165
	v_fma_f32 v61, v61, v231, -v165
	v_fma_f32 v62, v62, v232, -v165
	v_fma_f32 v63, v63, v233, -v165
	v_exp_f32_e32 v48, v48
	v_exp_f32_e32 v49, v49
	v_exp_f32_e32 v50, v50
	v_exp_f32_e32 v51, v51
	v_exp_f32_e32 v52, v52
	v_exp_f32_e32 v53, v53
	v_exp_f32_e32 v54, v54
	v_exp_f32_e32 v55, v55
	v_exp_f32_e32 v56, v56
	v_exp_f32_e32 v57, v57
	v_exp_f32_e32 v58, v58
	v_exp_f32_e32 v59, v59
	v_exp_f32_e32 v60, v60
	v_exp_f32_e32 v61, v61
	v_exp_f32_e32 v62, v62
	v_exp_f32_e32 v63, v63
	v_add_f32_e32 v234, v64, v48
	v_add_f32_e32 v235, v65, v49
	v_add_f32_e32 v236, v66, v50
	v_add_f32_e32 v237, v67, v51
	v_add_f32_e32 v238, v68, v52
	v_add_f32_e32 v239, v69, v53
	v_add_f32_e32 v240, v70, v54
	v_add_f32_e32 v241, v71, v55
	v_add_f32_e32 v242, v72, v56
	v_add_f32_e32 v243, v73, v57
	v_add_f32_e32 v244, v74, v58
	v_add_f32_e32 v245, v75, v59
	v_add_f32_e32 v246, v76, v60
	v_add_f32_e32 v247, v77, v61
	v_add_f32_e32 v248, v78, v62
	v_add_f32_e32 v249, v79, v63
	v_add_f32_e32 v234, v234, v235
	v_add_f32_e32 v236, v236, v237
	v_add_f32_e32 v238, v238, v239
	v_add_f32_e32 v240, v240, v241
	v_add_f32_e32 v242, v242, v243
	v_add_f32_e32 v244, v244, v245
	v_add_f32_e32 v246, v246, v247
	v_add_f32_e32 v248, v248, v249
	v_add_f32_e32 v234, v234, v236
	v_add_f32_e32 v238, v238, v240
	v_add_f32_e32 v242, v242, v244
	v_add_f32_e32 v246, v246, v248
	v_add_f32_e32 v234, v234, v238
	v_add_f32_e32 v242, v242, v246
	v_add_f32_e32 v234, v234, v242
	v_cvt_pk_bf16_f32 v64, v64, v65
	v_cvt_pk_bf16_f32 v65, v66, v67
	v_cvt_pk_bf16_f32 v66, v68, v69
	v_cvt_pk_bf16_f32 v67, v70, v71
	v_cvt_pk_bf16_f32 v68, v72, v73
	v_cvt_pk_bf16_f32 v69, v74, v75
	v_cvt_pk_bf16_f32 v70, v76, v77
	v_cvt_pk_bf16_f32 v71, v78, v79
	v_cvt_pk_bf16_f32 v48, v48, v49
	v_cvt_pk_bf16_f32 v49, v50, v51
	v_cvt_pk_bf16_f32 v50, v52, v53
	v_cvt_pk_bf16_f32 v51, v54, v55
	v_cvt_pk_bf16_f32 v52, v56, v57
	v_cvt_pk_bf16_f32 v53, v58, v59
	v_cvt_pk_bf16_f32 v54, v60, v61
	v_cvt_pk_bf16_f32 v55, v62, v63
	v_add_f32_e32 v151, v151, v234
.Latt2_yskip_h1p0:
	s_add_i32 s49, s49, 1
	s_barrier
	s_cmp_gt_i32 s49, s48
	s_cbranch_scc1 .Latt2_h1p1_xin
	s_bitcmp1_b32 s49, 0
	s_cselect_b32 s53, 0x5900, 0
	v_add3_u32 v157, s53, v190, v191
	v_add_u32_e32 v1, s53, v193
	v_add3_u32 v229, s53, v192, v191
	ds_read_b128 v[72:75], v157
	ds_read_b128 v[56:59], v157 offset:6656
	v_mfma_f32_32x32x16_bf16 v[32:47], v[128:131], v[64:67], v[32:47]
	ds_read_b128 v[230:233], v157 offset:32
	ds_read_b128 v[234:237], v157 offset:6688
	v_mfma_f32_32x32x16_bf16 v[16:31], v[210:213], v[64:67], v[16:31]
	ds_read_b128 v[238:241], v157 offset:64
	ds_read_b128 v[242:245], v157 offset:6720
	v_mfma_f32_32x32x16_bf16 v[32:47], v[124:127], v[68:71], v[32:47]
	ds_read_b128 v[246:249], v157 offset:96
	ds_read_b128 v[250:253], v157 offset:6752
	v_mfma_f32_32x32x16_bf16 v[16:31], v[120:123], v[68:71], v[16:31]
	ds_read_b128 v[214:217], v157 offset:128
	ds_read_b128 v[128:131], v157 offset:6784
	v_mfma_f32_32x32x16_bf16 v[32:47], v[116:119], v[48:51], v[32:47]
	ds_read_b128 v[210:213], v157 offset:160
	v_mfma_f32_32x32x16_bf16 v[16:31], v[112:115], v[48:51], v[16:31]
	ds_read_b128 v[124:127], v157 offset:6816
	v_mfma_f32_32x32x16_bf16 v[32:47], v[108:111], v[52:55], v[32:47]
	v_mfma_f32_32x32x16_bf16 v[16:31], v[10:13], v[52:55], v[16:31]

.Latt2_P_11:
	s_bitcmp0_b32 s49, 0
	s_cselect_b32 s53, 0x5900, 0
	v_add3_u32 v1, s53, v143, v134
	s_cmp_lg_u64 s[44:45], 0
	s_cbranch_scc0 .Latt2_S_o_11
	s_waitcnt vmcnt(5)
	ds_write_b128 v1, v[2:5]
	v_add_f32_e32 v1, v153, v155
	v_fmamk_f32 v1, v1, 0x3c2aaaab, v207
	v_rsq_f32_e32 v1, v1
	v_add_u32_e32 v157, s53, v187
	s_nop 0
	ds_write_b32 v157, v1 offset:21504
	s_waitcnt vmcnt(4)
	s_branch .Latt2_S_j_11
.Latt2_S_o_11:
	s_waitcnt vmcnt(3)
	ds_write_b128 v1, v[2:5]
	s_waitcnt vmcnt(2)
.Latt2_S_j_11:
	v_add3_u32 v1, s53, v189, v134
	ds_write_b128 v1, v[6:9] offset:13312
	s_add_i32 s53, s49, 3
	s_cmp_gt_u32 s53, s47
	s_cbranch_scc1 .Latt2_h1p1_xend
	global_load_dwordx4 v[2:5], v[182:183], off
	s_cmp_lg_u64 s[44:45], 0
	s_cbranch_scc0 .Latt2_L_v_12
	v_ashrrev_i32_e32 v181, 31, v180
	v_lshl_add_u64 v[6:7], v[180:181], 2, s[8:9]
	v_ashrrev_i32_e32 v179, 31, v178
	global_load_dword v153, v[6:7], off
	v_lshl_add_u64 v[6:7], v[178:179], 2, s[22:23]
	global_load_dword v155, v[6:7], off

.Latt2_h1_exit:
	s_cmp_lg_u32 s48, s47
	s_cbranch_scc1 .Latt2_exit
	s_waitcnt lgkmcnt(0)
	v_mfma_f32_32x32x16_bf16 v[32:47], v[128:131], v[64:67], v[32:47]
	v_mfma_f32_32x32x16_bf16 v[16:31], v[210:213], v[64:67], v[16:31]
	v_mfma_f32_32x32x16_bf16 v[32:47], v[124:127], v[68:71], v[32:47]
	v_mfma_f32_32x32x16_bf16 v[16:31], v[120:123], v[68:71], v[16:31]
	v_mfma_f32_32x32x16_bf16 v[32:47], v[116:119], v[48:51], v[32:47]
	v_mfma_f32_32x32x16_bf16 v[16:31], v[112:115], v[48:51], v[16:31]
	v_mfma_f32_32x32x16_bf16 v[32:47], v[108:111], v[52:55], v[32:47]
	v_mfma_f32_32x32x16_bf16 v[16:31], v[10:13], v[52:55], v[16:31]
.Latt2_exit:
	v_lshlrev_b32_e32 v1, 4, v164
	v_add_u32_e32 v1, 0x14000, v1
	ds_read_b128 v[194:197], v1
	ds_read_b128 v[198:201], v1 offset:8192
	ds_read_b128 v[202:205], v1 offset:16384
	s_waitcnt lgkmcnt(0)
	s_branch .LBB0_44
	s_nop 0
	s_nop 0
	s_nop 0
	s_nop 0
	s_nop 0
	s_nop 0
	s_nop 0
	s_nop 0
	s_nop 0
	s_nop 0
	s_nop 0
	s_nop 0
	s_nop 0
	s_nop 0
	s_nop 0
	s_nop 0
	s_nop 0
	s_nop 0
	s_nop 0
	s_nop 0
	s_nop 0
	s_nop 0
	s_nop 0
	s_nop 0
	s_nop 0
	s_nop 0
	s_nop 0
	s_nop 0
	s_nop 0
	s_nop 0
	s_nop 0
	s_nop 0
	s_nop 0
	s_nop 0
	s_nop 0
	s_nop 0
	s_nop 0
	s_nop 0
	s_nop 0
	s_nop 0
	s_nop 0
	s_nop 0
	s_nop 0

.Lepi_noprojn:
	s_cmp_eq_u32 s31, 8
	s_cbranch_scc1 .Lepi_w1
	s_branch .Lepi_projt
.LBB0_441:
.LBB0_442:
.LBB0_444:
.LBB0_445:
.LBB0_447:
.LBB0_448:
.LBB0_451:
.LBB0_453:
.LBB0_454:
.LBB0_460:
.LBB0_461:
.LBB0_463:
.LBB0_464:
.LBB0_466:
.LBB0_467:
.LBB0_470:
.LBB0_479:
.LBB0_480:
.LBB0_482:
.LBB0_483:
.LBB0_486:
.LBB0_487:
.LBB0_488:
.LBB0_491:
.LBB0_493:
.LBB0_494:
.LBB0_495:
.LBB0_497:
.LBB0_499:
.LBB0_500:
.LBB0_506:
.LBB0_507:
.LBB0_509:
.LBB0_510:
.LBB0_512:
.LBB0_513:
.LBB0_516:
.LBB0_518:
.LBB0_519:
.LBB0_525:
.LBB0_526:
.LBB0_528:
.LBB0_529:
.LBB0_531:
.LBB0_532:
.LBB0_535:
.LBB0_544:
.LBB0_545:
.LBB0_547:
.LBB0_548:
.LBB0_551:
.LBB0_552:
.LBB0_553:
.LBB0_556:
.LBB0_558:
.LBB0_559:
.LBB0_560:
.LBB0_562:
.LBB0_564:
.LBB0_565:
.LBB0_571:
.LBB0_572:
.LBB0_574:
.LBB0_575:
.LBB0_577:
.LBB0_578:
.LBB0_581:
.LBB0_583:
.LBB0_584:
.LBB0_590:
.LBB0_591:
.LBB0_593:
.LBB0_594:
.LBB0_596:
.LBB0_597:
.LBB0_600:
.LBB0_602:
.LBB0_603:
.LBB0_608:
.LBB0_609:
.LBB0_611:
.LBB0_612:
.LBB0_614:
.LBB0_615:
.LBB0_618:
.LBB0_620:
.LBB0_621:
.LBB0_627:
.LBB0_628:
.LBB0_630:
.LBB0_631:
.LBB0_633:
.LBB0_634:
.LBB0_637:
.LBB0_646:
.LBB0_647:
.LBB0_649:
.LBB0_650:
.LBB0_653:
.LBB0_654:
.LBB0_655:
.LBB0_658:
.LBB0_660:
.LBB0_661:
.LBB0_662:
.LBB0_664:
.LBB0_666:
.LBB0_667:
.LBB0_673:
.LBB0_674:
.LBB0_676:
.LBB0_677:
.LBB0_679:
.LBB0_680:
.LBB0_683:
.LBB0_685:
.LBB0_686:
.LBB0_692:
.LBB0_693:
.LBB0_695:
.LBB0_696:
.LBB0_698:
.LBB0_699:
.LBB0_702:
.LBB0_704:
.LBB0_705:
.LBB0_710:
.LBB0_711:
.LBB0_713:
.LBB0_714:
.LBB0_716:
.LBB0_717:
.LBB0_720:
.LBB0_722:
.LBB0_723:
.LBB0_729:
.LBB0_730:
.LBB0_732:
.LBB0_733:
.LBB0_735:
.LBB0_736:
.LBB0_739:
.LBB0_748:
.LBB0_749:
.LBB0_751:
.LBB0_752:
.LBB0_755:
.LBB0_756:
.LBB0_757:
.LBB0_760:
.LBB0_762:
.LBB0_763:
.LBB0_764:
.LBB0_766:
.LBB0_768:
.LBB0_769:
.LBB0_775:
.LBB0_776:
.LBB0_778:
.LBB0_779:
.LBB0_781:
.LBB0_782:
.LBB0_785:
.LBB0_787:
.LBB0_788:
.LBB0_794:
.LBB0_795:
.LBB0_797:
.LBB0_798:
.LBB0_800:
.LBB0_801:
.LBB0_804:
.LBB0_806:
.LBB0_807:
.LBB0_812:
.LBB0_813:
.LBB0_815:
.LBB0_816:
.LBB0_818:
.LBB0_819:
.LBB0_822:
.LBB0_824:
.LBB0_825:
.LBB0_831:
.LBB0_832:
.LBB0_834:
.LBB0_835:
.LBB0_837:
.LBB0_838:
.LBB0_841:
.LBB0_850:
.LBB0_851:
.LBB0_853:
.LBB0_854:
.LBB0_857:
.LBB0_858:
.LBB0_859:
.LBB0_862:
.LBB0_864:
.LBB0_865:
.LBB0_866:
.LBB0_868:
.LBB0_870:
.LBB0_871:
.LBB0_877:
.LBB0_878:
.LBB0_880:
.LBB0_881:
.LBB0_883:
.LBB0_884:
.LBB0_887:
.LBB0_889:
.LBB0_890:
.LBB0_896:
.LBB0_897:
.LBB0_899:
.LBB0_900:
.LBB0_902:
.LBB0_903:
.LBB0_906:
.LBB0_908:
.LBB0_909:
.LBB0_914:
.LBB0_915:
.LBB0_917:
.LBB0_918:
.LBB0_920:
.LBB0_921:
.LBB0_924:
.LBB0_926:
.LBB0_927:
.LBB0_933:
.LBB0_934:
.LBB0_936:
.LBB0_937:
.LBB0_939:
.LBB0_940:
.LBB0_943:
.LBB0_952:
.LBB0_953:
.LBB0_955:
.LBB0_956:
.LBB0_959:
.LBB0_960:
.LBB0_961:
.LBB0_964:
.LBB0_966:
.LBB0_967:
.LBB0_968:
.LBB0_970:
.LBB0_972:
.LBB0_973:
.LBB0_979:
.LBB0_980:
.LBB0_982:
.LBB0_983:
.LBB0_985:
.LBB0_986:
.LBB0_989:
.LBB0_991:
.LBB0_992:
.LBB0_998:
.LBB0_999:
.LBB0_1001:
.LBB0_1002:
.LBB0_1004:
.LBB0_1005:
.LBB0_1008:
.LBB0_1010:
.LBB0_1011:
.LBB0_1016:
.LBB0_1017:
.LBB0_1019:
.LBB0_1020:
.LBB0_1022:
.LBB0_1023:
.LBB0_1026:
.LBB0_1028:
.LBB0_1029:
.LBB0_1035:
.LBB0_1036:
.LBB0_1038:
.LBB0_1039:
.LBB0_1041:
.LBB0_1042:
.LBB0_1045:
.LBB0_1054:
.LBB0_1055:
.LBB0_1057:
.LBB0_1058:
.LBB0_1061:
.LBB0_1062:
.LBB0_1063:
.LBB0_1066:
.LBB0_1068:
.LBB0_1069:
.LBB0_1070:
.LBB0_1072:
.LBB0_1074:
.LBB0_1075:
.LBB0_1081:
.LBB0_1082:
.LBB0_1084:
.LBB0_1085:
.LBB0_1087:
.LBB0_1088:
.LBB0_1091:
.LBB0_1093:
.LBB0_1094:
.LBB0_1100:
.LBB0_1101:
.LBB0_1103:
.LBB0_1104:
.LBB0_1106:
.LBB0_1107:
.LBB0_1110:
.LBB0_1112:
.LBB0_1113:
.LBB0_1118:
.LBB0_1119:
.LBB0_1121:
.LBB0_1122:
.LBB0_1124:
.LBB0_1125:
.LBB0_1128:
.LBB0_1130:
.LBB0_1131:
.LBB0_1137:
.LBB0_1138:
.LBB0_1140:
.LBB0_1141:
.LBB0_1143:
.LBB0_1144:
.LBB0_1147:
.LBB0_1156:
.LBB0_1157:
.LBB0_1159:
.LBB0_1160:
.LBB0_1163:
.LBB0_1164:
.LBB0_1165:
.LBB0_1168:
.LBB0_1170:
.LBB0_1171:
.LBB0_1172:
.LBB0_1174:
.LBB0_1176:
.LBB0_1177:
.LBB0_1183:
.LBB0_1184:
.LBB0_1186:
.LBB0_1187:
.LBB0_1189:
.LBB0_1190:
.LBB0_1193:
.LBB0_1195:
.LBB0_1196:
.LBB0_1202:
.LBB0_1203:
.LBB0_1205:
.LBB0_1206:
.LBB0_1208:
.LBB0_1209:
.LBB0_1212:
.LBB0_1214:
.LBB0_1215:
.LBB0_1220:
.LBB0_1221:
.LBB0_1223:
.LBB0_1224:
.LBB0_1226:
.LBB0_1227:
.LBB0_1230:
.LBB0_1232:
.LBB0_1233:
.LBB0_1239:
.LBB0_1240:
.LBB0_1242:
.LBB0_1243:
.LBB0_1245:
.LBB0_1246:
.LBB0_1249:
.LBB0_1251:
	s_mov_b64 s[46:47], -1
	s_and_b64 vcc, exec, s[44:45]
	s_cbranch_vccz .LBB0_419

.LBB0_1254:
.LBB0_1261:
.LBB0_1262:
.LBB0_1264:
.LBB0_1265:
.LBB0_1268:
.LBB0_1269:
.LBB0_1270:
.LBB0_1273:
.LBB0_1275:
.LBB0_1276:
.LBB0_1277:
.LBB0_1279:
.LBB0_1281:
.LBB0_1282:
.LBB0_1289:
.LBB0_1290:
.LBB0_1292:
.LBB0_1293:
.LBB0_1296:
.LBB0_1297:
.LBB0_1298:
.LBB0_1301:
.LBB0_1303:
.LBB0_1304:
.LBB0_1305:
.LBB0_1307:
.LBB0_1309:
.LBB0_1310:
.LBB0_1317:
.LBB0_1318:
.LBB0_1320:
.LBB0_1321:
.LBB0_1324:
.LBB0_1325:
.LBB0_1326:
.LBB0_1329:
.LBB0_1331:
.LBB0_1332:
.LBB0_1333:
.LBB0_1335:
.LBB0_1337:
.LBB0_1338:
.LBB0_1345:
.LBB0_1346:
.LBB0_1348:
.LBB0_1349:
.LBB0_1352:
.LBB0_1353:
.LBB0_1354:
.LBB0_1357:
.LBB0_1359:
.LBB0_1360:
.LBB0_1361:
.LBB0_1363:
.LBB0_1365:
.LBB0_1366:
.LBB0_1373:
.LBB0_1374:
.LBB0_1376:
.LBB0_1377:
.LBB0_1380:
.LBB0_1381:
.LBB0_1382:
.LBB0_1385:
.LBB0_1387:
.LBB0_1388:
.LBB0_1389:
.LBB0_1391:
.LBB0_1393:
.LBB0_1394:
.LBB0_1401:
.LBB0_1402:
.LBB0_1404:
.LBB0_1405:
.LBB0_1408:
.LBB0_1409:
.LBB0_1410:
.LBB0_1413:
.LBB0_1415:
.LBB0_1416:
.LBB0_1417:
.LBB0_1419:
.LBB0_1421:
.LBB0_1422:
.LBB0_1429:
.LBB0_1430:
.LBB0_1432:
.LBB0_1433:
.LBB0_1436:
.LBB0_1437:
.LBB0_1438:
.LBB0_1441:
.LBB0_1443:
.LBB0_1444:
.LBB0_1445:
.LBB0_1447:
.LBB0_1449:
.LBB0_1450:
.LBB0_1457:
.LBB0_1458:
.LBB0_1460:
.LBB0_1461:
.LBB0_1464:
.LBB0_1465:
.LBB0_1466:
.LBB0_1469:
.LBB0_1471:
.LBB0_1472:
.LBB0_1473:
.LBB0_1475:
.LBB0_1477:
.LBB0_1478:
	s_waitcnt vmcnt(0)
	v_readlane_b32 s70, v255, 15
	v_readlane_b32 s72, v255, 17
	v_readlane_b32 s74, v255, 20
	v_readlane_b32 s76, v255, 22
	v_readlane_b32 s78, v255, 24
	v_readlane_b32 s80, v255, 26
	v_readlane_b32 s92, v255, 28
	v_readlane_b32 s54, v255, 12
	v_readlane_b32 s62, v255, 38
	v_readlane_b32 s68, v255, 14
	v_readlane_b32 s71, v255, 16
	v_readlane_b32 s73, v255, 18
	v_readlane_b32 s69, v255, 19
	v_readlane_b32 s75, v255, 21
	v_readlane_b32 s77, v255, 23
	v_readlane_b32 s79, v255, 25
	v_readlane_b32 s81, v255, 27
	v_readlane_b32 s93, v255, 29
	v_readlane_b32 s55, v255, 13
	s_movk_i32 s82, 0x90
	s_movk_i32 s85, 0x80
	v_readlane_b32 s27, v255, 31
	v_readlane_b32 s63, v255, 39
	s_barrier

.LBB0_1603:
.Lgemm_zero_skip:
	v_mov_b32_e32 v129, 0
	v_mov_b32_e32 v128, v129
	v_mov_b32_e32 v127, v129
	v_mov_b32_e32 v126, v129
	v_mov_b32_e32 v125, v129
	v_mov_b32_e32 v124, v129
	v_mov_b32_e32 v123, v129
	v_mov_b32_e32 v122, v129
	v_mov_b32_e32 v113, v129
	v_mov_b32_e32 v112, v129
	v_mov_b32_e32 v111, v129
	v_mov_b32_e32 v110, v129
	v_mov_b32_e32 v109, v129
	v_mov_b32_e32 v108, v129
	v_mov_b32_e32 v107, v129
	v_mov_b32_e32 v106, v129
	v_mov_b32_e32 v97, v129
	v_mov_b32_e32 v96, v129
	v_mov_b32_e32 v95, v129
	v_mov_b32_e32 v94, v129
	v_mov_b32_e32 v93, v129
	v_mov_b32_e32 v92, v129
	v_mov_b32_e32 v91, v129
	v_mov_b32_e32 v90, v129
	v_mov_b32_e32 v81, v129
	v_mov_b32_e32 v80, v129
	v_mov_b32_e32 v79, v129
	v_mov_b32_e32 v78, v129
	v_mov_b32_e32 v77, v129
	v_mov_b32_e32 v76, v129
	v_mov_b32_e32 v75, v129
	v_mov_b32_e32 v74, v129
	v_mov_b32_e32 v121, v129
	v_mov_b32_e32 v120, v129
	v_mov_b32_e32 v119, v129
	v_mov_b32_e32 v118, v129
	v_mov_b32_e32 v117, v129
	v_mov_b32_e32 v116, v129
	v_mov_b32_e32 v115, v129
	v_mov_b32_e32 v114, v129
	v_mov_b32_e32 v105, v129
	v_mov_b32_e32 v104, v129
	v_mov_b32_e32 v103, v129
	v_mov_b32_e32 v102, v129
	v_mov_b32_e32 v101, v129
	v_mov_b32_e32 v100, v129
	v_mov_b32_e32 v99, v129
	v_mov_b32_e32 v98, v129
	v_mov_b32_e32 v89, v129
	v_mov_b32_e32 v88, v129
	v_mov_b32_e32 v87, v129
	v_mov_b32_e32 v86, v129
	v_mov_b32_e32 v85, v129
	v_mov_b32_e32 v84, v129
	v_mov_b32_e32 v83, v129
	v_mov_b32_e32 v82, v129
	v_mov_b32_e32 v73, v129
	v_mov_b32_e32 v72, v129
	v_mov_b32_e32 v71, v129
	v_mov_b32_e32 v70, v129
	v_mov_b32_e32 v69, v129
	v_mov_b32_e32 v68, v129
	v_mov_b32_e32 v67, v129
	v_mov_b32_e32 v66, v129
	v_mov_b32_e32 v65, v129
	v_mov_b32_e32 v64, v129
	v_mov_b32_e32 v63, v129
	v_mov_b32_e32 v62, v129
	v_mov_b32_e32 v61, v129
	v_mov_b32_e32 v60, v129
	v_mov_b32_e32 v59, v129
	v_mov_b32_e32 v58, v129
	v_mov_b32_e32 v49, v129
	v_mov_b32_e32 v48, v129
	v_mov_b32_e32 v47, v129
	v_mov_b32_e32 v46, v129
	v_mov_b32_e32 v45, v129
	v_mov_b32_e32 v44, v129
	v_mov_b32_e32 v43, v129
	v_mov_b32_e32 v42, v129
	v_mov_b32_e32 v33, v129
	v_mov_b32_e32 v32, v129
	v_mov_b32_e32 v31, v129
	v_mov_b32_e32 v30, v129
	v_mov_b32_e32 v29, v129
	v_mov_b32_e32 v28, v129
	v_mov_b32_e32 v27, v129
	v_mov_b32_e32 v26, v129
	v_mov_b32_e32 v17, v129
	v_mov_b32_e32 v16, v129
	v_mov_b32_e32 v15, v129
	v_mov_b32_e32 v14, v129
	v_mov_b32_e32 v13, v129
	v_mov_b32_e32 v12, v129
	v_mov_b32_e32 v11, v129
	v_mov_b32_e32 v10, v129
	v_mov_b32_e32 v57, v129
	v_mov_b32_e32 v56, v129
	v_mov_b32_e32 v55, v129
	v_mov_b32_e32 v54, v129
	v_mov_b32_e32 v53, v129
	v_mov_b32_e32 v52, v129
	v_mov_b32_e32 v51, v129
	v_mov_b32_e32 v50, v129
	v_mov_b32_e32 v41, v129
	v_mov_b32_e32 v40, v129
	v_mov_b32_e32 v39, v129
	v_mov_b32_e32 v38, v129
	v_mov_b32_e32 v37, v129
	v_mov_b32_e32 v36, v129
	v_mov_b32_e32 v35, v129
	v_mov_b32_e32 v34, v129
	v_mov_b32_e32 v25, v129
	v_mov_b32_e32 v24, v129
	v_mov_b32_e32 v23, v129
	v_mov_b32_e32 v22, v129
	v_mov_b32_e32 v21, v129
	v_mov_b32_e32 v20, v129
	v_mov_b32_e32 v19, v129
	v_mov_b32_e32 v18, v129
	v_mov_b32_e32 v9, v129
	v_mov_b32_e32 v8, v129
	v_mov_b32_e32 v7, v129
	v_mov_b32_e32 v6, v129
	v_mov_b32_e32 v5, v129
	v_mov_b32_e32 v4, v129
	v_mov_b32_e32 v3, v129
	v_mov_b32_e32 v2, v129
	s_branch .LBB0_433
